# attention tile loops: 192 packed v_pk_add_f32 (softmax subtract / row-sum) split into scalar v_sub/v_add pairs (bit-identical); on top of EW LDS staging + BR epilogue
# speedup vs baseline: 1.0030x; 1.0030x over previous
.LBB0_159:
	v_mov_b32_e32 v183, v182
	v_sub_f32_e32 v64, v64, v182
	v_sub_f32_e32 v65, v65, v183
	v_sub_f32_e32 v66, v66, v182
	v_sub_f32_e32 v67, v67, v183
	v_exp_f32_e32 v64, v64
	v_exp_f32_e32 v65, v65
	v_exp_f32_e32 v66, v66
	v_exp_f32_e32 v67, v67
	v_sub_f32_e32 v68, v68, v182
	v_sub_f32_e32 v69, v69, v183
	v_sub_f32_e32 v70, v70, v182
	v_sub_f32_e32 v71, v71, v183
	v_exp_f32_e32 v68, v68
	v_exp_f32_e32 v69, v69
	v_exp_f32_e32 v70, v70
	v_exp_f32_e32 v71, v71
	v_sub_f32_e32 v72, v72, v182
	v_sub_f32_e32 v73, v73, v183
	v_add_f32_e32 v82, 0, v64
	v_add_f32_e32 v83, 0, v65
	v_exp_f32_e32 v72, v72
	v_exp_f32_e32 v73, v73
	v_sub_f32_e32 v74, v74, v182
	v_sub_f32_e32 v75, v75, v183
	v_add_f32_e32 v82, v66, v82
	v_add_f32_e32 v83, v67, v83
	v_exp_f32_e32 v74, v74
	v_exp_f32_e32 v75, v75
	v_sub_f32_e32 v76, v76, v182
	v_sub_f32_e32 v77, v77, v183
	v_add_f32_e32 v82, v68, v82
	v_add_f32_e32 v83, v69, v83
	v_exp_f32_e32 v76, v76
	v_exp_f32_e32 v77, v77
	v_sub_f32_e32 v78, v78, v182
	v_sub_f32_e32 v79, v79, v183
	v_add_f32_e32 v82, v70, v82
	v_add_f32_e32 v83, v71, v83
	v_exp_f32_e32 v78, v78
	v_exp_f32_e32 v79, v79
	v_add_f32_e32 v82, v72, v82
	v_add_f32_e32 v83, v73, v83
	v_cvt_pk_bf16_f32 v64, v64, v65
	v_add_f32_e32 v82, v74, v82
	v_add_f32_e32 v83, v75, v83
	v_cvt_pk_bf16_f32 v65, v66, v67
	v_add_f32_e32 v82, v76, v82
	v_add_f32_e32 v83, v77, v83
	v_cvt_pk_bf16_f32 v66, v68, v69
	v_add_f32_e32 v82, v78, v82
	v_add_f32_e32 v83, v79, v83
	v_cvt_pk_bf16_f32 v67, v70, v71
	v_add_f32_e32 v90, v82, v83
	v_cvt_pk_bf16_f32 v68, v72, v73
	v_cvt_pk_bf16_f32 v69, v74, v75
	v_cvt_pk_bf16_f32 v70, v76, v77
	v_cvt_pk_bf16_f32 v71, v78, v79
	ds_read_b128 v[72:75], v80 offset:34880
	ds_read_b128 v[76:79], v80 offset:34912
	ds_read_b128 v[82:85], v80 offset:39488
	ds_read_b128 v[86:89], v80 offset:39520
	s_waitcnt lgkmcnt(3)
	v_mfma_f32_32x32x16_bf16 v[32:47], v[72:75], v[64:67], v[32:47]
	s_waitcnt lgkmcnt(1)
	v_mfma_f32_32x32x16_bf16 v[48:63], v[82:85], v[64:67], v[48:63]
	v_mfma_f32_32x32x16_bf16 v[32:47], v[76:79], v[68:71], v[32:47]
	s_waitcnt lgkmcnt(0)
	v_mfma_f32_32x32x16_bf16 v[48:63], v[86:89], v[68:71], v[48:63]
	ds_read_b128 v[72:75], v80 offset:44096
	ds_read_b128 v[76:79], v80 offset:44128
	ds_read_b128 v[82:85], v80 offset:48704
	ds_read_b128 v[86:89], v80 offset:48736
	s_waitcnt lgkmcnt(3)
	v_mfma_f32_32x32x16_bf16 v[16:31], v[72:75], v[64:67], v[16:31]
	s_waitcnt lgkmcnt(1)
	v_mfma_f32_32x32x16_bf16 v[0:15], v[82:85], v[64:67], v[0:15]
	v_mfma_f32_32x32x16_bf16 v[16:31], v[76:79], v[68:71], v[16:31]
	s_waitcnt lgkmcnt(0)
	v_mfma_f32_32x32x16_bf16 v[0:15], v[86:89], v[68:71], v[0:15]
	v_add_f32_e32 v179, v81, v90
	v_mov_b32_e32 v182, v196

; template <int MODE> ...
;     ...
;     const bool trailing = wid >= 4;
;     bf16x8 pa0, pb0, pa1, pb1; bool actp = false; int vsp = 0;
.LBB0_171:
	v_cndmask_b32_e64 v182, v214, v196, s[8:9]
	v_sub_f32_e32 v80, v80, v182
	v_sub_f32_e32 v81, v81, v182
	v_sub_f32_e32 v82, v82, v182
	v_sub_f32_e32 v83, v83, v182
	v_exp_f32_e32 v80, v80
	v_exp_f32_e32 v81, v81
	v_exp_f32_e32 v200, v82
	v_exp_f32_e32 v201, v83
	v_sub_f32_e32 v84, v84, v182
	v_sub_f32_e32 v85, v85, v182
	v_sub_f32_e32 v86, v86, v182
	v_sub_f32_e32 v87, v87, v182
	v_exp_f32_e32 v84, v84
	v_exp_f32_e32 v85, v85
	v_exp_f32_e32 v86, v86
	v_exp_f32_e32 v87, v87
	v_sub_f32_e32 v88, v88, v182
	v_sub_f32_e32 v89, v89, v182
	v_add_f32_e32 v198, 0, v80
	v_add_f32_e32 v199, 0, v81
	v_exp_f32_e32 v88, v88
	v_exp_f32_e32 v89, v89
	v_sub_f32_e32 v90, v90, v182
	v_sub_f32_e32 v91, v91, v182
	v_add_f32_e32 v82, v200, v198
	v_add_f32_e32 v83, v201, v199
	v_exp_f32_e32 v90, v90
	v_exp_f32_e32 v91, v91
	v_sub_f32_e32 v92, v92, v182
	v_sub_f32_e32 v93, v93, v182
	v_add_f32_e32 v82, v84, v82
	v_add_f32_e32 v83, v85, v83
	v_exp_f32_e32 v92, v92
	v_exp_f32_e32 v93, v93
	v_sub_f32_e32 v94, v94, v182
	v_sub_f32_e32 v95, v95, v182
	v_add_f32_e32 v82, v86, v82
	v_add_f32_e32 v83, v87, v83
	v_exp_f32_e32 v94, v94
	v_exp_f32_e32 v95, v95
	v_add_f32_e32 v82, v88, v82
	v_add_f32_e32 v83, v89, v83
	v_cvt_pk_bf16_f32 v84, v84, v85
	v_add_f32_e32 v82, v90, v82
	v_add_f32_e32 v83, v91, v83
	v_cvt_pk_bf16_f32 v85, v86, v87
	v_add_f32_e32 v82, v92, v82
	v_add_f32_e32 v83, v93, v83
	v_cvt_pk_bf16_f32 v86, v88, v89
	v_add_f32_e32 v82, v94, v82
	v_add_f32_e32 v83, v95, v83
	v_cvt_pk_bf16_f32 v87, v90, v91
	v_add_f32_e32 v197, v82, v83
	v_cvt_pk_bf16_f32 v82, v80, v81
	v_add_u32_e32 v80, s89, v193
	v_add_u32_e32 v80, v80, v160
	v_cvt_pk_bf16_f32 v83, v200, v201
	v_cvt_pk_bf16_f32 v88, v92, v93
	ds_read_b128 v[90:93], v80 offset:34816
	ds_read_b128 v[198:201], v80 offset:34848
	ds_read_b128 v[222:225], v80 offset:39424
	ds_read_b128 v[226:229], v80 offset:39456
	v_cvt_pk_bf16_f32 v89, v94, v95
	s_waitcnt lgkmcnt(3)
	v_mfma_f32_32x32x16_bf16 v[32:47], v[90:93], v[82:85], v[32:47]
	s_waitcnt lgkmcnt(1)
	v_mfma_f32_32x32x16_bf16 v[48:63], v[222:225], v[82:85], v[48:63]
	v_mfma_f32_32x32x16_bf16 v[32:47], v[198:201], v[86:89], v[32:47]
	s_waitcnt lgkmcnt(0)
	v_mfma_f32_32x32x16_bf16 v[48:63], v[226:229], v[86:89], v[48:63]
	ds_read_b128 v[90:93], v80 offset:44032
	ds_read_b128 v[198:201], v80 offset:44064
	ds_read_b128 v[222:225], v80 offset:48640
	ds_read_b128 v[226:229], v80 offset:48672
	s_waitcnt lgkmcnt(3)
	v_mfma_f32_32x32x16_bf16 v[16:31], v[90:93], v[82:85], v[16:31]
	s_waitcnt lgkmcnt(1)
	v_mfma_f32_32x32x16_bf16 v[0:15], v[222:225], v[82:85], v[0:15]
	v_mfma_f32_32x32x16_bf16 v[16:31], v[198:201], v[86:89], v[16:31]
	s_waitcnt lgkmcnt(0)
	v_mfma_f32_32x32x16_bf16 v[0:15], v[226:229], v[86:89], v[0:15]
	v_max_f32_e32 v82, v65, v65
	v_max_f32_e32 v83, v64, v64
	v_max_f32_e32 v82, v83, v82
	v_max3_f32 v82, v82, v66, v67
	v_max3_f32 v82, v82, v68, v69
	v_max3_f32 v82, v82, v70, v71
	v_max3_f32 v82, v82, v72, v73
	v_max3_f32 v82, v82, v74, v75
	v_max3_f32 v82, v82, v76, v77
	v_max3_f32 v82, v82, v78, v79
	v_mov_b32_e32 v83, v82
	s_nop 1
	v_permlane32_swap_b32_e32 v82, v83
	v_max_f32_e32 v83, v83, v83
	v_max_f32_e32 v82, v82, v82
	v_max_f32_e32 v82, v82, v83
	v_cndmask_b32_e64 v82, v213, v82, s[8:9]
	v_max_f32_e32 v83, v196, v196
	v_max_f32_e32 v82, v83, v82
	v_add_f32_e32 v81, v179, v197
	v_cmp_gt_f32_e32 vcc, v82, v183
	s_cbranch_vccz .LBB0_159
	v_sub_f32_e32 v83, v196, v82
	v_exp_f32_e32 v84, v83
	v_cndmask_b32_e64 v182, v214, v82, s[8:9]
	v_mov_b32_e32 v196, v82
	v_pk_mul_f32 v[46:47], v[46:47], v[84:85] op_sel_hi:[1,0]
	v_pk_mul_f32 v[44:45], v[44:45], v[84:85] op_sel_hi:[1,0]
	v_pk_mul_f32 v[42:43], v[42:43], v[84:85] op_sel_hi:[1,0]
	v_pk_mul_f32 v[40:41], v[40:41], v[84:85] op_sel_hi:[1,0]
	v_pk_mul_f32 v[38:39], v[38:39], v[84:85] op_sel_hi:[1,0]
	v_pk_mul_f32 v[36:37], v[36:37], v[84:85] op_sel_hi:[1,0]
	v_pk_mul_f32 v[34:35], v[34:35], v[84:85] op_sel_hi:[1,0]
	v_pk_mul_f32 v[32:33], v[32:33], v[84:85] op_sel_hi:[1,0]
	v_pk_mul_f32 v[62:63], v[62:63], v[84:85] op_sel_hi:[1,0]
	v_pk_mul_f32 v[60:61], v[60:61], v[84:85] op_sel_hi:[1,0]
	v_pk_mul_f32 v[58:59], v[58:59], v[84:85] op_sel_hi:[1,0]
	v_pk_mul_f32 v[56:57], v[56:57], v[84:85] op_sel_hi:[1,0]
	v_pk_mul_f32 v[54:55], v[54:55], v[84:85] op_sel_hi:[1,0]
	v_pk_mul_f32 v[52:53], v[52:53], v[84:85] op_sel_hi:[1,0]
	v_pk_mul_f32 v[50:51], v[50:51], v[84:85] op_sel_hi:[1,0]
	v_pk_mul_f32 v[48:49], v[48:49], v[84:85] op_sel_hi:[1,0]
	v_pk_mul_f32 v[30:31], v[30:31], v[84:85] op_sel_hi:[1,0]
	v_pk_mul_f32 v[28:29], v[28:29], v[84:85] op_sel_hi:[1,0]
	v_pk_mul_f32 v[26:27], v[26:27], v[84:85] op_sel_hi:[1,0]
	v_pk_mul_f32 v[24:25], v[24:25], v[84:85] op_sel_hi:[1,0]
	v_pk_mul_f32 v[22:23], v[22:23], v[84:85] op_sel_hi:[1,0]
	v_pk_mul_f32 v[20:21], v[20:21], v[84:85] op_sel_hi:[1,0]
	v_pk_mul_f32 v[18:19], v[18:19], v[84:85] op_sel_hi:[1,0]
	v_pk_mul_f32 v[16:17], v[16:17], v[84:85] op_sel_hi:[1,0]
	v_pk_mul_f32 v[14:15], v[14:15], v[84:85] op_sel_hi:[1,0]
	v_pk_mul_f32 v[12:13], v[12:13], v[84:85] op_sel_hi:[1,0]
	v_pk_mul_f32 v[10:11], v[10:11], v[84:85] op_sel_hi:[1,0]
	v_pk_mul_f32 v[8:9], v[8:9], v[84:85] op_sel_hi:[1,0]
	v_pk_mul_f32 v[6:7], v[6:7], v[84:85] op_sel_hi:[1,0]
	v_pk_mul_f32 v[4:5], v[4:5], v[84:85] op_sel_hi:[1,0]
	v_pk_mul_f32 v[2:3], v[2:3], v[84:85] op_sel_hi:[1,0]
	v_pk_mul_f32 v[0:1], v[0:1], v[84:85] op_sel_hi:[1,0]
	v_mul_f32_e32 v81, v81, v84
	s_branch .LBB0_159

.LBB0_189:
	v_cndmask_b32_e64 v152, v214, v151, s[6:7]
	v_sub_f32_e32 v80, v80, v152
	v_sub_f32_e32 v81, v81, v152
	v_sub_f32_e32 v82, v82, v152
	v_sub_f32_e32 v83, v83, v152
	v_exp_f32_e32 v80, v80
	v_exp_f32_e32 v81, v81
	v_exp_f32_e32 v82, v82
	v_exp_f32_e32 v83, v83
	v_sub_f32_e32 v84, v84, v152
	v_sub_f32_e32 v85, v85, v152
	v_sub_f32_e32 v86, v86, v152
	v_sub_f32_e32 v87, v87, v152
	v_exp_f32_e32 v84, v84
	v_exp_f32_e32 v85, v85
	v_exp_f32_e32 v86, v86
	v_exp_f32_e32 v87, v87
	v_sub_f32_e32 v88, v88, v152
	v_sub_f32_e32 v89, v89, v152
	v_add_f32_e32 v154, 0, v80
	v_add_f32_e32 v155, 0, v81
	v_exp_f32_e32 v88, v88
	v_exp_f32_e32 v89, v89
	v_sub_f32_e32 v90, v90, v152
	v_sub_f32_e32 v91, v91, v152
	v_add_f32_e32 v154, v82, v154
	v_add_f32_e32 v155, v83, v155
	v_exp_f32_e32 v90, v90
	v_exp_f32_e32 v91, v91
	v_sub_f32_e32 v92, v92, v152
	v_sub_f32_e32 v93, v93, v152
	v_add_f32_e32 v154, v84, v154
	v_add_f32_e32 v155, v85, v155
	v_exp_f32_e32 v92, v92
	v_exp_f32_e32 v93, v93
	v_sub_f32_e32 v94, v94, v152
	v_sub_f32_e32 v95, v95, v152
	v_add_f32_e32 v154, v86, v154
	v_add_f32_e32 v155, v87, v155
	v_exp_f32_e32 v94, v94
	v_exp_f32_e32 v95, v95
	v_sub_f32_e32 v64, v64, v152
	v_sub_f32_e32 v65, v65, v152
	v_add_f32_e32 v154, v88, v154
	v_add_f32_e32 v155, v89, v155
	v_exp_f32_e32 v64, v64
	v_exp_f32_e32 v65, v65
	v_sub_f32_e32 v66, v66, v152
	v_sub_f32_e32 v67, v67, v152
	v_add_f32_e32 v154, v90, v154
	v_add_f32_e32 v155, v91, v155
	v_exp_f32_e32 v66, v66
	v_exp_f32_e32 v67, v67
	v_sub_f32_e32 v68, v68, v152
	v_sub_f32_e32 v69, v69, v152
	v_add_f32_e32 v154, v92, v154
	v_add_f32_e32 v155, v93, v155
	v_exp_f32_e32 v68, v68
	v_exp_f32_e32 v69, v69
	v_sub_f32_e32 v70, v70, v152
	v_sub_f32_e32 v71, v71, v152
	v_add_f32_e32 v154, v94, v154
	v_add_f32_e32 v155, v95, v155
	v_exp_f32_e32 v70, v70
	v_exp_f32_e32 v71, v71
	v_sub_f32_e32 v72, v72, v152
	v_sub_f32_e32 v73, v73, v152
	v_cvt_pk_bf16_f32 v80, v80, v81
	v_cvt_pk_bf16_f32 v81, v82, v83
	v_cvt_pk_bf16_f32 v82, v84, v85
	v_cvt_pk_bf16_f32 v84, v88, v89
	v_add_f32_e32 v88, v64, v154
	v_add_f32_e32 v89, v65, v155
	v_exp_f32_e32 v72, v72
	v_exp_f32_e32 v73, v73
	v_sub_f32_e32 v74, v74, v152
	v_sub_f32_e32 v75, v75, v152
	v_add_f32_e32 v88, v66, v88
	v_add_f32_e32 v89, v67, v89
	v_exp_f32_e32 v74, v74
	v_exp_f32_e32 v75, v75
	v_sub_f32_e32 v76, v76, v152
	v_sub_f32_e32 v77, v77, v152
	v_add_f32_e32 v88, v68, v88
	v_add_f32_e32 v89, v69, v89
	v_exp_f32_e32 v76, v76
	v_exp_f32_e32 v77, v77
	v_sub_f32_e32 v78, v78, v152
	v_sub_f32_e32 v79, v79, v152
	v_add_f32_e32 v88, v70, v88
	v_add_f32_e32 v89, v71, v89
	v_exp_f32_e32 v78, v78
	v_exp_f32_e32 v79, v79
	v_add_f32_e32 v88, v72, v88
	v_add_f32_e32 v89, v73, v89
	v_cvt_pk_bf16_f32 v83, v86, v87
	v_add_f32_e32 v88, v74, v88
	v_add_f32_e32 v89, v75, v89
	v_cvt_pk_bf16_f32 v85, v90, v91
	v_add_f32_e32 v88, v76, v88
	v_add_f32_e32 v89, v77, v89
	v_cvt_pk_bf16_f32 v86, v92, v93
	v_add_f32_e32 v88, v78, v88
	v_add_f32_e32 v89, v79, v89
	v_cvt_pk_bf16_f32 v87, v94, v95
	v_add_f32_e32 v88, v88, v89
	v_add_f32_e32 v179, v179, v88
	v_cvt_pk_bf16_f32 v64, v64, v65
	v_cvt_pk_bf16_f32 v65, v66, v67
	v_cvt_pk_bf16_f32 v66, v68, v69
	v_cvt_pk_bf16_f32 v67, v70, v71
	v_cvt_pk_bf16_f32 v68, v72, v73
	v_cvt_pk_bf16_f32 v69, v74, v75
	v_cvt_pk_bf16_f32 v70, v76, v77
	v_cvt_pk_bf16_f32 v71, v78, v79

; template <int MODE> ...
;     ...
;     const bool trailing = wid >= 4;
;     bf16x8 pa0, pb0, pa1, pb1; bool actp = false; int vsp = 0;
.LBB0_232:
	v_cndmask_b32_e64 v182, v214, v196, s[8:9]
	v_sub_f32_e32 v80, v80, v182
	v_sub_f32_e32 v81, v81, v182
	v_sub_f32_e32 v82, v82, v182
	v_sub_f32_e32 v83, v83, v182
	v_exp_f32_e32 v80, v80
	v_exp_f32_e32 v81, v81
	v_exp_f32_e32 v200, v82
	v_exp_f32_e32 v201, v83
	v_sub_f32_e32 v84, v84, v182
	v_sub_f32_e32 v85, v85, v182
	v_sub_f32_e32 v86, v86, v182
	v_sub_f32_e32 v87, v87, v182
	v_exp_f32_e32 v84, v84
	v_exp_f32_e32 v85, v85
	v_exp_f32_e32 v86, v86
	v_exp_f32_e32 v87, v87
	v_sub_f32_e32 v88, v88, v182
	v_sub_f32_e32 v89, v89, v182
	v_add_f32_e32 v198, 0, v80
	v_add_f32_e32 v199, 0, v81
	v_exp_f32_e32 v88, v88
	v_exp_f32_e32 v89, v89
	v_sub_f32_e32 v90, v90, v182
	v_sub_f32_e32 v91, v91, v182
	v_add_f32_e32 v82, v200, v198
	v_add_f32_e32 v83, v201, v199
	v_exp_f32_e32 v90, v90
	v_exp_f32_e32 v91, v91
	v_sub_f32_e32 v92, v92, v182
	v_sub_f32_e32 v93, v93, v182
	v_add_f32_e32 v82, v84, v82
	v_add_f32_e32 v83, v85, v83
	v_exp_f32_e32 v92, v92
	v_exp_f32_e32 v93, v93
	v_sub_f32_e32 v94, v94, v182
	v_sub_f32_e32 v95, v95, v182
	v_add_f32_e32 v82, v86, v82
	v_add_f32_e32 v83, v87, v83
	v_exp_f32_e32 v94, v94
	v_exp_f32_e32 v95, v95
	v_add_f32_e32 v82, v88, v82
	v_add_f32_e32 v83, v89, v83
	v_cvt_pk_bf16_f32 v84, v84, v85
	v_add_f32_e32 v82, v90, v82
	v_add_f32_e32 v83, v91, v83
	v_cvt_pk_bf16_f32 v85, v86, v87
	v_add_f32_e32 v82, v92, v82
	v_add_f32_e32 v83, v93, v83
	v_cvt_pk_bf16_f32 v86, v88, v89
	v_add_f32_e32 v82, v94, v82
	v_add_f32_e32 v83, v95, v83
	v_cvt_pk_bf16_f32 v87, v90, v91
	v_add_f32_e32 v197, v82, v83
	v_cvt_pk_bf16_f32 v82, v80, v81
	v_add_u32_e32 v80, s79, v193
	v_add_u32_e32 v80, v80, v160
	v_cvt_pk_bf16_f32 v83, v200, v201
	v_cvt_pk_bf16_f32 v88, v92, v93
	ds_read_b128 v[90:93], v80 offset:34816
	ds_read_b128 v[198:201], v80 offset:34848
	ds_read_b128 v[222:225], v80 offset:39424
	ds_read_b128 v[226:229], v80 offset:39456
	v_cvt_pk_bf16_f32 v89, v94, v95
	s_waitcnt lgkmcnt(3)
	v_mfma_f32_32x32x16_bf16 v[32:47], v[90:93], v[82:85], v[32:47]
	s_waitcnt lgkmcnt(1)
	v_mfma_f32_32x32x16_bf16 v[48:63], v[222:225], v[82:85], v[48:63]
	v_mfma_f32_32x32x16_bf16 v[32:47], v[198:201], v[86:89], v[32:47]
	s_waitcnt lgkmcnt(0)
	v_mfma_f32_32x32x16_bf16 v[48:63], v[226:229], v[86:89], v[48:63]
	ds_read_b128 v[90:93], v80 offset:44032
	ds_read_b128 v[198:201], v80 offset:44064
	ds_read_b128 v[222:225], v80 offset:48640
	ds_read_b128 v[226:229], v80 offset:48672
	s_waitcnt lgkmcnt(3)
	v_mfma_f32_32x32x16_bf16 v[16:31], v[90:93], v[82:85], v[16:31]
	s_waitcnt lgkmcnt(1)
	v_mfma_f32_32x32x16_bf16 v[0:15], v[222:225], v[82:85], v[0:15]
	v_mfma_f32_32x32x16_bf16 v[16:31], v[198:201], v[86:89], v[16:31]
	s_waitcnt lgkmcnt(0)
	v_mfma_f32_32x32x16_bf16 v[0:15], v[226:229], v[86:89], v[0:15]
	v_max_f32_e32 v82, v65, v65
	v_max_f32_e32 v83, v64, v64
	v_max_f32_e32 v82, v83, v82
	v_max3_f32 v82, v82, v66, v67
	v_max3_f32 v82, v82, v68, v69
	v_max3_f32 v82, v82, v70, v71
	v_max3_f32 v82, v82, v72, v73
	v_max3_f32 v82, v82, v74, v75
	v_max3_f32 v82, v82, v76, v77
	v_max3_f32 v82, v82, v78, v79
	v_mov_b32_e32 v83, v82
	s_nop 1
	v_permlane32_swap_b32_e32 v82, v83
	v_max_f32_e32 v83, v83, v83
	v_max_f32_e32 v82, v82, v82
	v_max_f32_e32 v82, v82, v83
	v_cndmask_b32_e64 v82, v213, v82, s[8:9]
	v_max_f32_e32 v83, v196, v196
	v_max_f32_e32 v82, v83, v82
	v_add_f32_e32 v81, v179, v197
	v_cmp_gt_f32_e32 vcc, v82, v183
	s_cbranch_vccz .LBB0_220
	v_sub_f32_e32 v83, v196, v82
	v_exp_f32_e32 v84, v83
	v_cndmask_b32_e64 v182, v214, v82, s[8:9]
	v_mov_b32_e32 v196, v82
	v_pk_mul_f32 v[46:47], v[46:47], v[84:85] op_sel_hi:[1,0]
	v_pk_mul_f32 v[44:45], v[44:45], v[84:85] op_sel_hi:[1,0]
	v_pk_mul_f32 v[42:43], v[42:43], v[84:85] op_sel_hi:[1,0]
	v_pk_mul_f32 v[40:41], v[40:41], v[84:85] op_sel_hi:[1,0]
	v_pk_mul_f32 v[38:39], v[38:39], v[84:85] op_sel_hi:[1,0]
	v_pk_mul_f32 v[36:37], v[36:37], v[84:85] op_sel_hi:[1,0]
	v_pk_mul_f32 v[34:35], v[34:35], v[84:85] op_sel_hi:[1,0]
	v_pk_mul_f32 v[32:33], v[32:33], v[84:85] op_sel_hi:[1,0]
	v_pk_mul_f32 v[62:63], v[62:63], v[84:85] op_sel_hi:[1,0]
	v_pk_mul_f32 v[60:61], v[60:61], v[84:85] op_sel_hi:[1,0]
	v_pk_mul_f32 v[58:59], v[58:59], v[84:85] op_sel_hi:[1,0]
	v_pk_mul_f32 v[56:57], v[56:57], v[84:85] op_sel_hi:[1,0]
	v_pk_mul_f32 v[54:55], v[54:55], v[84:85] op_sel_hi:[1,0]
	v_pk_mul_f32 v[52:53], v[52:53], v[84:85] op_sel_hi:[1,0]
	v_pk_mul_f32 v[50:51], v[50:51], v[84:85] op_sel_hi:[1,0]
	v_pk_mul_f32 v[48:49], v[48:49], v[84:85] op_sel_hi:[1,0]
	v_pk_mul_f32 v[30:31], v[30:31], v[84:85] op_sel_hi:[1,0]
	v_pk_mul_f32 v[28:29], v[28:29], v[84:85] op_sel_hi:[1,0]
	v_pk_mul_f32 v[26:27], v[26:27], v[84:85] op_sel_hi:[1,0]
	v_pk_mul_f32 v[24:25], v[24:25], v[84:85] op_sel_hi:[1,0]
	v_pk_mul_f32 v[22:23], v[22:23], v[84:85] op_sel_hi:[1,0]
	v_pk_mul_f32 v[20:21], v[20:21], v[84:85] op_sel_hi:[1,0]
	v_pk_mul_f32 v[18:19], v[18:19], v[84:85] op_sel_hi:[1,0]
	v_pk_mul_f32 v[16:17], v[16:17], v[84:85] op_sel_hi:[1,0]
	v_pk_mul_f32 v[14:15], v[14:15], v[84:85] op_sel_hi:[1,0]
	v_pk_mul_f32 v[12:13], v[12:13], v[84:85] op_sel_hi:[1,0]
	v_pk_mul_f32 v[10:11], v[10:11], v[84:85] op_sel_hi:[1,0]
	v_pk_mul_f32 v[8:9], v[8:9], v[84:85] op_sel_hi:[1,0]
	v_pk_mul_f32 v[6:7], v[6:7], v[84:85] op_sel_hi:[1,0]
	v_pk_mul_f32 v[4:5], v[4:5], v[84:85] op_sel_hi:[1,0]
	v_pk_mul_f32 v[2:3], v[2:3], v[84:85] op_sel_hi:[1,0]
	v_pk_mul_f32 v[0:1], v[0:1], v[84:85] op_sel_hi:[1,0]
	v_mul_f32_e32 v81, v81, v84
	s_branch .LBB0_220

.LBB0_267:
	v_mov_b32_e32 v81, v168
	v_sub_f32_e32 v64, v64, v80
	v_sub_f32_e32 v65, v65, v81
	v_sub_f32_e32 v66, v66, v80
	v_sub_f32_e32 v67, v67, v81
	v_exp_f32_e32 v64, v64
	v_exp_f32_e32 v65, v65
	v_exp_f32_e32 v66, v66
	v_exp_f32_e32 v67, v67
	v_sub_f32_e32 v68, v68, v80
	v_sub_f32_e32 v69, v69, v81
	v_sub_f32_e32 v70, v70, v80
	v_sub_f32_e32 v71, v71, v81
	v_exp_f32_e32 v68, v68
	v_exp_f32_e32 v69, v69
	v_exp_f32_e32 v70, v70
	v_exp_f32_e32 v71, v71
	v_sub_f32_e32 v72, v72, v80
	v_sub_f32_e32 v73, v73, v81
	v_add_f32_e32 v84, 0, v64
	v_add_f32_e32 v85, 0, v65
	v_exp_f32_e32 v72, v72
	v_exp_f32_e32 v73, v73
	v_sub_f32_e32 v74, v74, v80
	v_sub_f32_e32 v75, v75, v81
	v_add_f32_e32 v84, v66, v84
	v_add_f32_e32 v85, v67, v85
	v_exp_f32_e32 v74, v74
	v_exp_f32_e32 v75, v75
	v_sub_f32_e32 v76, v76, v80
	v_sub_f32_e32 v77, v77, v81
	v_add_f32_e32 v84, v68, v84
	v_add_f32_e32 v85, v69, v85
	v_exp_f32_e32 v76, v76
	v_exp_f32_e32 v77, v77
	v_sub_f32_e32 v78, v78, v80
	v_sub_f32_e32 v79, v79, v81
	v_add_f32_e32 v84, v70, v84
	v_add_f32_e32 v85, v71, v85
	v_exp_f32_e32 v78, v78
	v_exp_f32_e32 v79, v79
	v_add_f32_e32 v84, v72, v84
	v_add_f32_e32 v85, v73, v85
	v_cvt_pk_bf16_f32 v64, v64, v65
	v_add_f32_e32 v84, v74, v84
	v_add_f32_e32 v85, v75, v85
	v_cvt_pk_bf16_f32 v65, v66, v67
	v_add_f32_e32 v84, v76, v84
	v_add_f32_e32 v85, v77, v85
	v_cvt_pk_bf16_f32 v66, v68, v69
	v_add_f32_e32 v80, v78, v84
	v_add_f32_e32 v81, v79, v85
	v_cvt_pk_bf16_f32 v67, v70, v71
	v_cvt_pk_bf16_f32 v68, v72, v73
	v_cvt_pk_bf16_f32 v69, v74, v75
	v_cvt_pk_bf16_f32 v70, v76, v77
	v_cvt_pk_bf16_f32 v71, v78, v79
	ds_read_b128 v[72:75], v82 offset:34880
	ds_read_b128 v[76:79], v82 offset:34912
	ds_read_b128 v[84:87], v82 offset:39488
	ds_read_b128 v[88:91], v82 offset:39520
	v_add_f32_e32 v80, v80, v81
	s_waitcnt lgkmcnt(3)
	v_mfma_f32_32x32x16_bf16 v[48:63], v[72:75], v[64:67], v[48:63]
	s_waitcnt lgkmcnt(1)
	v_mfma_f32_32x32x16_bf16 v[32:47], v[84:87], v[64:67], v[32:47]
	v_mfma_f32_32x32x16_bf16 v[48:63], v[76:79], v[68:71], v[48:63]
	s_waitcnt lgkmcnt(0)
	v_mfma_f32_32x32x16_bf16 v[32:47], v[88:91], v[68:71], v[32:47]
	ds_read_b128 v[72:75], v82 offset:44096
	ds_read_b128 v[76:79], v82 offset:44128
	ds_read_b128 v[84:87], v82 offset:48704
	ds_read_b128 v[88:91], v82 offset:48736
	s_waitcnt lgkmcnt(3)
	v_mfma_f32_32x32x16_bf16 v[16:31], v[72:75], v[64:67], v[16:31]
	s_waitcnt lgkmcnt(1)
	v_mfma_f32_32x32x16_bf16 v[0:15], v[84:87], v[64:67], v[0:15]
	v_mfma_f32_32x32x16_bf16 v[16:31], v[76:79], v[68:71], v[16:31]
	s_waitcnt lgkmcnt(0)
	v_mfma_f32_32x32x16_bf16 v[0:15], v[88:91], v[68:71], v[0:15]
	v_add_f32_e32 v172, v83, v80
	v_mov_b32_e32 v173, v168

.LBB0_275:
	v_sub_f32_e32 v80, v80, v168
	v_sub_f32_e32 v81, v81, v168
	v_sub_f32_e32 v82, v82, v168
	v_sub_f32_e32 v83, v83, v168
	v_exp_f32_e32 v80, v80
	v_exp_f32_e32 v81, v81
	v_exp_f32_e32 v82, v82
	v_exp_f32_e32 v83, v83
	v_sub_f32_e32 v84, v84, v168
	v_sub_f32_e32 v85, v85, v168
	v_add_f32_e32 v176, 0, v80
	v_add_f32_e32 v177, 0, v81
	v_exp_f32_e32 v178, v84
	v_exp_f32_e32 v179, v85
	v_add_f32_e32 v176, v82, v176
	v_add_f32_e32 v177, v83, v177
	v_sub_f32_e32 v86, v86, v168
	v_sub_f32_e32 v87, v87, v168
	v_add_f32_e32 v84, v178, v176
	v_add_f32_e32 v85, v179, v177
	v_exp_f32_e32 v176, v86
	v_exp_f32_e32 v177, v87
	v_sub_f32_e32 v86, v88, v168
	v_sub_f32_e32 v87, v89, v168
	v_add_f32_e32 v84, v176, v84
	v_add_f32_e32 v85, v177, v85
	v_exp_f32_e32 v88, v86
	v_exp_f32_e32 v89, v87
	v_sub_f32_e32 v86, v90, v168
	v_sub_f32_e32 v87, v91, v168
	v_add_f32_e32 v84, v88, v84
	v_add_f32_e32 v85, v89, v85
	v_exp_f32_e32 v90, v86
	v_exp_f32_e32 v91, v87
	v_sub_f32_e32 v86, v92, v168
	v_sub_f32_e32 v87, v93, v168
	v_cvt_pk_bf16_f32 v88, v88, v89
	v_exp_f32_e32 v92, v86
	v_exp_f32_e32 v93, v87
	v_sub_f32_e32 v86, v94, v168
	v_sub_f32_e32 v87, v95, v168
	v_add_f32_e32 v84, v90, v84
	v_add_f32_e32 v85, v91, v85
	v_exp_f32_e32 v94, v86
	v_exp_f32_e32 v95, v87
	v_add_f32_e32 v84, v92, v84
	v_add_f32_e32 v85, v93, v85
	v_cvt_pk_bf16_f32 v86, v178, v179
	v_cvt_pk_bf16_f32 v87, v176, v177
	v_add_f32_e32 v84, v94, v84
	v_add_f32_e32 v85, v95, v85
	v_cvt_pk_bf16_f32 v89, v90, v91
	v_add_f32_e32 v173, v84, v85
	v_cvt_pk_bf16_f32 v84, v80, v81
	v_add_u32_e32 v80, s88, v157
	v_cvt_pk_bf16_f32 v85, v82, v83
	v_add_u32_e32 v82, v80, v160
	v_cvt_pk_bf16_f32 v90, v92, v93
	v_cvt_pk_bf16_f32 v91, v94, v95
	ds_read_b128 v[92:95], v82 offset:34816
	ds_read_b128 v[176:179], v82 offset:34848
	ds_read_b128 v[180:183], v82 offset:39424
	ds_read_b128 v[186:189], v82 offset:39456
	s_waitcnt lgkmcnt(3)
	v_mfma_f32_32x32x16_bf16 v[48:63], v[92:95], v[84:87], v[48:63]
	s_waitcnt lgkmcnt(1)
	v_mfma_f32_32x32x16_bf16 v[32:47], v[180:183], v[84:87], v[32:47]
	v_mfma_f32_32x32x16_bf16 v[48:63], v[176:179], v[88:91], v[48:63]
	s_waitcnt lgkmcnt(0)
	v_mfma_f32_32x32x16_bf16 v[32:47], v[186:189], v[88:91], v[32:47]
	ds_read_b128 v[92:95], v82 offset:44032
	ds_read_b128 v[176:179], v82 offset:44064
	ds_read_b128 v[180:183], v82 offset:48640
	ds_read_b128 v[186:189], v82 offset:48672
	s_waitcnt lgkmcnt(3)
	v_mfma_f32_32x32x16_bf16 v[16:31], v[92:95], v[84:87], v[16:31]
	s_waitcnt lgkmcnt(1)
	v_mfma_f32_32x32x16_bf16 v[0:15], v[180:183], v[84:87], v[0:15]
	v_mfma_f32_32x32x16_bf16 v[16:31], v[176:179], v[88:91], v[16:31]
	s_waitcnt lgkmcnt(0)
	v_mfma_f32_32x32x16_bf16 v[0:15], v[186:189], v[88:91], v[0:15]
	v_max_f32_e32 v80, v65, v65
	v_max_f32_e32 v81, v64, v64
	v_max_f32_e32 v80, v81, v80
	v_max3_f32 v80, v80, v66, v67
	v_max3_f32 v80, v80, v68, v69
	v_max3_f32 v80, v80, v70, v71
	v_max3_f32 v80, v80, v72, v73
	v_max3_f32 v80, v80, v74, v75
	v_max3_f32 v80, v80, v76, v77
	v_max3_f32 v80, v80, v78, v79
	v_mov_b32_e32 v81, v80
	s_nop 1
	v_permlane32_swap_b32_e32 v80, v81
	v_max3_f32 v80, v168, v80, v81
	v_add_f32_e32 v83, v172, v173
	v_cmp_gt_f32_e32 vcc, v80, v174
	s_cbranch_vccnz .LBB0_266
	v_mov_b64_e32 v[80:81], v[168:169]
	s_branch .LBB0_267

.LBB0_288:
	v_sub_f32_e32 v80, v80, v128
	v_sub_f32_e32 v81, v81, v128
	v_sub_f32_e32 v82, v82, v128
	v_sub_f32_e32 v83, v83, v128
	v_exp_f32_e32 v80, v80
	v_exp_f32_e32 v81, v81
	v_exp_f32_e32 v82, v82
	v_exp_f32_e32 v83, v83
	v_sub_f32_e32 v84, v84, v128
	v_sub_f32_e32 v85, v85, v128
	v_sub_f32_e32 v86, v86, v128
	v_sub_f32_e32 v87, v87, v128
	v_exp_f32_e32 v84, v84
	v_exp_f32_e32 v85, v85
	v_exp_f32_e32 v86, v86
	v_exp_f32_e32 v87, v87
	v_sub_f32_e32 v88, v88, v128
	v_sub_f32_e32 v89, v89, v128
	v_add_f32_e32 v130, 0, v80
	v_add_f32_e32 v131, 0, v81
	v_exp_f32_e32 v88, v88
	v_exp_f32_e32 v89, v89
	v_sub_f32_e32 v90, v90, v128
	v_sub_f32_e32 v91, v91, v128
	v_add_f32_e32 v130, v82, v130
	v_add_f32_e32 v131, v83, v131
	v_exp_f32_e32 v90, v90
	v_exp_f32_e32 v91, v91
	v_sub_f32_e32 v92, v92, v128
	v_sub_f32_e32 v93, v93, v128
	v_add_f32_e32 v130, v84, v130
	v_add_f32_e32 v131, v85, v131
	v_exp_f32_e32 v92, v92
	v_exp_f32_e32 v93, v93
	v_sub_f32_e32 v94, v94, v128
	v_sub_f32_e32 v95, v95, v128
	v_add_f32_e32 v130, v86, v130
	v_add_f32_e32 v131, v87, v131
	v_exp_f32_e32 v94, v94
	v_exp_f32_e32 v95, v95
	v_sub_f32_e32 v64, v64, v128
	v_sub_f32_e32 v65, v65, v128
	v_add_f32_e32 v130, v88, v130
	v_add_f32_e32 v131, v89, v131
	v_exp_f32_e32 v64, v64
	v_exp_f32_e32 v65, v65
	v_sub_f32_e32 v66, v66, v128
	v_sub_f32_e32 v67, v67, v128
	v_add_f32_e32 v130, v90, v130
	v_add_f32_e32 v131, v91, v131
	v_exp_f32_e32 v66, v66
	v_exp_f32_e32 v67, v67
	v_sub_f32_e32 v68, v68, v128
	v_sub_f32_e32 v69, v69, v128
	v_add_f32_e32 v130, v92, v130
	v_add_f32_e32 v131, v93, v131
	v_exp_f32_e32 v68, v68
	v_exp_f32_e32 v69, v69
	v_sub_f32_e32 v70, v70, v128
	v_sub_f32_e32 v71, v71, v128
	v_add_f32_e32 v130, v94, v130
	v_add_f32_e32 v131, v95, v131
	v_exp_f32_e32 v70, v70
	v_exp_f32_e32 v71, v71
	v_sub_f32_e32 v72, v72, v128
	v_sub_f32_e32 v73, v73, v128
	v_cvt_pk_bf16_f32 v80, v80, v81
	v_cvt_pk_bf16_f32 v81, v82, v83
	v_cvt_pk_bf16_f32 v82, v84, v85
	v_cvt_pk_bf16_f32 v84, v88, v89
	v_add_f32_e32 v88, v64, v130
	v_add_f32_e32 v89, v65, v131
	v_exp_f32_e32 v72, v72
	v_exp_f32_e32 v73, v73
	v_sub_f32_e32 v74, v74, v128
	v_sub_f32_e32 v75, v75, v128
	v_add_f32_e32 v88, v66, v88
	v_add_f32_e32 v89, v67, v89
	v_exp_f32_e32 v74, v74
	v_exp_f32_e32 v75, v75
	v_sub_f32_e32 v76, v76, v128
	v_sub_f32_e32 v77, v77, v128
	v_add_f32_e32 v88, v68, v88
	v_add_f32_e32 v89, v69, v89
	v_exp_f32_e32 v76, v76
	v_exp_f32_e32 v77, v77
	v_sub_f32_e32 v78, v78, v128
	v_sub_f32_e32 v79, v79, v128
	v_add_f32_e32 v88, v70, v88
	v_add_f32_e32 v89, v71, v89
	v_exp_f32_e32 v78, v78
	v_exp_f32_e32 v79, v79
	v_add_f32_e32 v88, v72, v88
	v_add_f32_e32 v89, v73, v89
	v_cvt_pk_bf16_f32 v83, v86, v87
	v_add_f32_e32 v88, v74, v88
	v_add_f32_e32 v89, v75, v89
	v_cvt_pk_bf16_f32 v85, v90, v91
	v_add_f32_e32 v88, v76, v88
	v_add_f32_e32 v89, v77, v89
	v_cvt_pk_bf16_f32 v86, v92, v93
	v_add_f32_e32 v88, v78, v88
	v_add_f32_e32 v89, v79, v89
	v_cvt_pk_bf16_f32 v87, v94, v95
	v_add_f32_e32 v88, v88, v89
	v_add_f32_e32 v172, v172, v88
	v_cvt_pk_bf16_f32 v64, v64, v65
	v_cvt_pk_bf16_f32 v65, v66, v67
	v_cvt_pk_bf16_f32 v66, v68, v69
	v_cvt_pk_bf16_f32 v67, v70, v71
	v_cvt_pk_bf16_f32 v68, v72, v73
	v_cvt_pk_bf16_f32 v69, v74, v75
	v_cvt_pk_bf16_f32 v70, v76, v77
	v_cvt_pk_bf16_f32 v71, v78, v79
	v_mov_b32_e32 v130, v128
